# norm row loops: xor-32 and xor-16 butterfly steps via v_permlane32_swap / v_permlane16_swap (no LDS round trips left in the row reduction)
# baseline (speedup 1.0000x reference)
; DI unsigned pack2(float a, float b) { f2_t v = {a, b}; return __builtin_bit_cast(unsigned, __builtin_convertvector(v, bf2_t)); }
; DI float wave_sum(float v) {
; #pragma unroll
;   for (int o = 32; o >= 1; o >>= 1) v += __shfl_xor(v, o);
;   return v;
; template <int MODE>
; DI void phase_norm(const float* xin, const float* g, const float* modl, int sh_off, int sc_off, u16* hout, float* fout) {
;     ...
;   for (int row = blockIdx.x * NWAVE + w; row < NTOK; row += gridDim.x * NWAVE) {
;     const int b = row >> 14;
;     const float4* xr = (const float4*)(xin + (size_t)row * 1024);
;     float4 v[4];
; #pragma unroll
;     for (int i = 0; i < 4; ++i) v[i] = xr[lane + i * 64];
;     float ss = 0.f;
; #pragma unroll
;     for (int i = 0; i < 4; ++i) ss += v[i].x * v[i].x + v[i].y * v[i].y + v[i].z * v[i].z + v[i].w * v[i].w;
;     ss = wave_sum(ss);
;     const float inv = rsqrtf(ss * (1.f / 1024.f) + 1e-6f);
; #pragma unroll
;     for (int i = 0; i < 4; ++i) {
;       const int col = (lane + i * 64) * 4;
;       const float4 g4 = *(const float4*)(g + col);
;       if (MODE == 0) {
;         const float4 sc4 = *(const float4*)(modl + b * 6144 + sc_off + col);
;         const float4 sh4 = *(const float4*)(modl + b * 6144 + sh_off + col);
;         float y0 = v[i].x * inv * g4.x * (1.f + sc4.x) + sh4.x;
;         float y1 = v[i].y * inv * g4.y * (1.f + sc4.y) + sh4.y;
;         float y2 = v[i].z * inv * g4.z * (1.f + sc4.z) + sh4.z;
;         float y3 = v[i].w * inv * g4.w * (1.f + sc4.w) + sh4.w;
;         *(uint2*)(hout + (size_t)row * 1024 + col) = make_uint2(pack2(y0, y1), pack2(y2, y3));
.LBB0_55:
	v_ashrrev_i32_e32 v3, 31, v2
	v_lshlrev_b64 v[38:39], 12, v[2:3]
	v_lshl_add_u64 v[50:51], v[6:7], 0, v[38:39]
	global_load_dwordx4 v[38:41], v[50:51], off
	global_load_dwordx4 v[42:45], v[50:51], off offset:1024
	global_load_dwordx4 v[46:49], v[50:51], off offset:2048
	s_nop 0
	global_load_dwordx4 v[50:53], v[50:51], off offset:3072
	v_ashrrev_i32_e32 v54, 14, v2
	v_mul_i32_i24_e32 v54, 0x1800, v54
	v_ashrrev_i32_e32 v55, 31, v54
	v_lshl_add_u64 v[62:63], v[54:55], 2, s[26:27]
	s_mov_b64 s[6:7], 0x1000
	v_lshl_add_u64 v[66:67], v[62:63], 0, s[6:7]
	v_lshl_add_u64 v[54:55], v[66:67], 0, v[0:1]
	global_load_dwordx4 v[54:57], v[54:55], off
	s_nop 0
	global_load_dwordx4 v[58:61], v[4:5], off
	v_lshl_add_u64 v[68:69], v[62:63], 0, v[0:1]
	global_load_dwordx4 v[62:65], v[68:69], off
	v_lshl_add_u64 v[122:123], v[66:67], 0, v[10:11]
	v_lshl_add_u64 v[124:125], v[66:67], 0, v[12:13]
	v_lshl_add_u64 v[126:127], v[66:67], 0, v[14:15]
	global_load_dwordx4 v[86:89], v[4:5], off offset:1024
	global_load_dwordx4 v[90:93], v[122:123], off
	global_load_dwordx4 v[94:97], v[68:69], off offset:1024
	global_load_dwordx4 v[98:101], v[4:5], off offset:2048
	global_load_dwordx4 v[102:105], v[124:125], off
	global_load_dwordx4 v[106:109], v[68:69], off offset:2048
	global_load_dwordx4 v[110:113], v[4:5], off offset:3072
	global_load_dwordx4 v[114:117], v[126:127], off
	global_load_dwordx4 v[118:121], v[68:69], off offset:3072
	s_waitcnt vmcnt(15)
	v_mov_b32_e32 v76, v39
	s_waitcnt vmcnt(14)
	v_mov_b32_e32 v77, v43
	v_mov_b32_e32 v74, v38
	v_mov_b32_e32 v75, v42
	s_waitcnt vmcnt(13)
	v_mov_b32_e32 v84, v47
	s_waitcnt vmcnt(12)
	v_mov_b32_e32 v85, v51
	v_pk_mul_f32 v[76:77], v[76:77], v[76:77]
	v_mov_b32_e32 v70, v40
	v_mov_b32_e32 v71, v44
	v_mov_b32_e32 v82, v46
	v_mov_b32_e32 v83, v50
	v_pk_mul_f32 v[84:85], v[84:85], v[84:85]
	v_pk_fma_f32 v[74:75], v[74:75], v[74:75], v[76:77]
	v_mov_b32_e32 v72, v41
	v_mov_b32_e32 v73, v45
	v_mov_b32_e32 v78, v48
	v_mov_b32_e32 v79, v52
	v_pk_fma_f32 v[76:77], v[82:83], v[82:83], v[84:85]
	v_pk_fma_f32 v[70:71], v[70:71], v[70:71], v[74:75]
	v_mov_b32_e32 v80, v49
	v_mov_b32_e32 v81, v53
	v_pk_fma_f32 v[74:75], v[78:79], v[78:79], v[76:77]
	v_pk_fma_f32 v[70:71], v[72:73], v[72:73], v[70:71]
	v_pk_fma_f32 v[72:73], v[80:81], v[80:81], v[74:75]
	v_add_f32_e32 v70, v70, v71
	v_add_f32_e32 v70, v70, v72
	v_add_f32_e32 v70, v70, v73
	v_mov_b32_e32 v71, v70
	s_waitcnt vmcnt(11)
	v_pk_add_f32 v[54:55], v[54:55], 1.0 op_sel_hi:[1,0]
	v_pk_add_f32 v[56:57], v[56:57], 1.0 op_sel_hi:[1,0]
	s_nop 1
	v_permlane32_swap_b32_e32 v71, v70
	s_nop 0
	v_add_f32_e32 v70, v70, v71
	v_mov_b32_e32 v71, v70
	s_nop 1
	v_permlane16_swap_b32_e32 v71, v70
	s_nop 0
	v_add_f32_e32 v70, v70, v71
	s_nop 1
	v_add_f32_dpp v70, v70, v70 row_ror:8 row_mask:0xf bank_mask:0xf
	s_nop 1
	v_add_f32_dpp v70, v70, v70 row_ror:4 row_mask:0xf bank_mask:0xf
	s_nop 1
	v_add_f32_dpp v72, v70, v70 row_ror:2 row_mask:0xf bank_mask:0xf
	v_lshlrev_b64 v[70:71], 11, v[2:3]
	v_lshl_add_u64 v[70:71], v[8:9], 0, v[70:71]
	v_add_u32_e32 v2, s3, v2
	s_nop 1
	v_add_f32_dpp v3, v72, v72 row_ror:1 row_mask:0xf bank_mask:0xf
	v_fmamk_f32 v3, v3, 0x3a800000, v225
	v_mul_f32_e32 v72, 0x4b800000, v3
	v_cmp_gt_f32_e32 vcc, s33, v3
	s_nop 1
	v_cndmask_b32_e32 v3, v3, v72, vcc
	v_rsq_f32_e32 v3, v3
	v_lshl_add_u64 v[72:73], v[66:67], 0, v[10:11]
	v_mul_f32_e32 v74, 0x45800000, v3
	v_cndmask_b32_e32 v74, v3, v74, vcc
	v_pk_mul_f32 v[38:39], v[38:39], v[74:75] op_sel_hi:[1,0]
	v_pk_mul_f32 v[40:41], v[40:41], v[74:75] op_sel_hi:[1,0]
	s_waitcnt vmcnt(10)
	v_pk_mul_f32 v[38:39], v[58:59], v[38:39]
	v_pk_mul_f32 v[40:41], v[60:61], v[40:41]
	s_waitcnt vmcnt(0)
	v_pk_fma_f32 v[38:39], v[54:55], v[38:39], v[62:63]
	v_pk_fma_f32 v[40:41], v[56:57], v[40:41], v[64:65]
	v_cvt_pk_bf16_f32 v38, v38, v39
	v_cvt_pk_bf16_f32 v39, v40, v41
	global_store_dwordx2 v[70:71], v[38:39], off
	s_nop 0
	v_pk_mul_f32 v[42:43], v[42:43], v[74:75] op_sel_hi:[1,0]
	v_pk_mul_f32 v[44:45], v[44:45], v[74:75] op_sel_hi:[1,0]
	v_lshl_add_u64 v[62:63], v[66:67], 0, v[12:13]
	v_pk_mul_f32 v[46:47], v[46:47], v[74:75] op_sel_hi:[1,0]
	v_pk_mul_f32 v[48:49], v[48:49], v[74:75] op_sel_hi:[1,0]
	v_pk_mul_f32 v[50:51], v[50:51], v[74:75] op_sel_hi:[1,0]
	v_pk_mul_f32 v[52:53], v[52:53], v[74:75] op_sel_hi:[1,0]
	v_cmp_lt_i32_e32 vcc, s94, v2
	s_or_b64 s[28:29], vcc, s[28:29]
	v_pk_mul_f32 v[38:39], v[42:43], v[86:87]
	v_pk_add_f32 v[42:43], v[90:91], 1.0 op_sel_hi:[1,0]
	v_pk_mul_f32 v[40:41], v[44:45], v[88:89]
	v_pk_add_f32 v[44:45], v[92:93], 1.0 op_sel_hi:[1,0]
	v_pk_fma_f32 v[38:39], v[38:39], v[42:43], v[94:95]
	v_pk_fma_f32 v[40:41], v[40:41], v[44:45], v[96:97]
	v_cvt_pk_bf16_f32 v38, v38, v39
	v_cvt_pk_bf16_f32 v39, v40, v41
	global_store_dwordx2 v[70:71], v[38:39], off offset:512
	s_nop 0
	v_lshl_add_u64 v[58:59], v[66:67], 0, v[14:15]
	v_pk_mul_f32 v[38:39], v[46:47], v[98:99]
	v_pk_add_f32 v[42:43], v[102:103], 1.0 op_sel_hi:[1,0]
	v_pk_mul_f32 v[40:41], v[48:49], v[100:101]
	v_pk_add_f32 v[44:45], v[104:105], 1.0 op_sel_hi:[1,0]
	v_pk_fma_f32 v[38:39], v[38:39], v[42:43], v[106:107]
	v_pk_fma_f32 v[40:41], v[40:41], v[44:45], v[108:109]
	v_cvt_pk_bf16_f32 v38, v38, v39
	v_cvt_pk_bf16_f32 v39, v40, v41
	global_store_dwordx2 v[70:71], v[38:39], off offset:1024
	s_nop 0
	v_pk_mul_f32 v[38:39], v[50:51], v[110:111]
	v_pk_add_f32 v[42:43], v[114:115], 1.0 op_sel_hi:[1,0]
	v_pk_mul_f32 v[40:41], v[52:53], v[112:113]
	v_pk_add_f32 v[44:45], v[116:117], 1.0 op_sel_hi:[1,0]
	v_pk_fma_f32 v[38:39], v[38:39], v[42:43], v[118:119]
	v_pk_fma_f32 v[40:41], v[40:41], v[44:45], v[120:121]
	v_cvt_pk_bf16_f32 v38, v38, v39
	v_cvt_pk_bf16_f32 v39, v40, v41
	global_store_dwordx2 v[70:71], v[38:39], off offset:1536
	s_andn2_b64 exec, exec, s[28:29]
	s_cbranch_execnz .LBB0_55

; DI unsigned pack2(float a, float b) { f2_t v = {a, b}; return __builtin_bit_cast(unsigned, __builtin_convertvector(v, bf2_t)); }
; DI float wave_sum(float v) {
; #pragma unroll
;   for (int o = 32; o >= 1; o >>= 1) v += __shfl_xor(v, o);
;   return v;
; template <int MODE>
; DI void phase_norm(const float* xin, const float* g, const float* modl, int sh_off, int sc_off, u16* hout, float* fout) {
;     ...
;   for (int row = blockIdx.x * NWAVE + w; row < NTOK; row += gridDim.x * NWAVE) {
;     const int b = row >> 14;
;     const float4* xr = (const float4*)(xin + (size_t)row * 1024);
;     float4 v[4];
; #pragma unroll
;     for (int i = 0; i < 4; ++i) v[i] = xr[lane + i * 64];
;     float ss = 0.f;
; #pragma unroll
;     for (int i = 0; i < 4; ++i) ss += v[i].x * v[i].x + v[i].y * v[i].y + v[i].z * v[i].z + v[i].w * v[i].w;
;     ss = wave_sum(ss);
;     const float inv = rsqrtf(ss * (1.f / 1024.f) + 1e-6f);
; #pragma unroll
;     for (int i = 0; i < 4; ++i) {
;       const int col = (lane + i * 64) * 4;
;       const float4 g4 = *(const float4*)(g + col);
;       if (MODE == 0) {
;         const float4 sc4 = *(const float4*)(modl + b * 6144 + sc_off + col);
;         const float4 sh4 = *(const float4*)(modl + b * 6144 + sh_off + col);
;         float y0 = v[i].x * inv * g4.x * (1.f + sc4.x) + sh4.x;
;         float y1 = v[i].y * inv * g4.y * (1.f + sc4.y) + sh4.y;
;         float y2 = v[i].z * inv * g4.z * (1.f + sc4.z) + sh4.z;
;         float y3 = v[i].w * inv * g4.w * (1.f + sc4.w) + sh4.w;
;         *(uint2*)(hout + (size_t)row * 1024 + col) = make_uint2(pack2(y0, y1), pack2(y2, y3));
.LBB0_597:
	v_ashrrev_i32_e32 v3, 31, v2
	v_lshlrev_b64 v[32:33], 12, v[2:3]
	v_lshl_add_u64 v[44:45], v[6:7], 0, v[32:33]
	global_load_dwordx4 v[32:35], v[44:45], off
	global_load_dwordx4 v[36:39], v[44:45], off offset:1024
	global_load_dwordx4 v[40:43], v[44:45], off offset:2048
	s_nop 0
	global_load_dwordx4 v[44:47], v[44:45], off offset:3072
	v_ashrrev_i32_e32 v11, 14, v2
	v_mul_i32_i24_e32 v48, 0x1800, v11
	v_ashrrev_i32_e32 v49, 31, v48
	v_lshl_add_u64 v[56:57], v[48:49], 2, s[24:25]
	s_mov_b64 s[6:7], 0x4000
	v_lshl_add_u64 v[60:61], v[56:57], 0, s[6:7]
	s_mov_b64 s[6:7], 0x3000
	v_lshl_add_u64 v[48:49], v[60:61], 0, v[0:1]
	v_lshl_add_u64 v[62:63], v[56:57], 0, s[6:7]
	global_load_dwordx4 v[48:51], v[48:49], off
	s_nop 0
	global_load_dwordx4 v[52:55], v[4:5], off
	v_lshl_add_u64 v[56:57], v[62:63], 0, v[0:1]
	global_load_dwordx4 v[56:59], v[56:57], off
	v_mov_b32_e32 v128, v10
	v_mov_b32_e32 v129, v1
	v_mov_b32_e32 v130, v12
	v_mov_b32_e32 v131, v1
	v_mov_b32_e32 v132, v14
	v_mov_b32_e32 v133, v1
	v_lshl_add_u64 v[134:135], v[60:61], 0, v[128:129]
	v_lshl_add_u64 v[136:137], v[62:63], 0, v[128:129]
	v_lshl_add_u64 v[138:139], v[60:61], 0, v[130:131]
	v_lshl_add_u64 v[140:141], v[62:63], 0, v[130:131]
	v_lshl_add_u64 v[142:143], v[60:61], 0, v[132:133]
	v_lshl_add_u64 v[144:145], v[62:63], 0, v[132:133]
	global_load_dwordx4 v[86:89], v[4:5], off offset:1024
	global_load_dwordx4 v[90:93], v[134:135], off
	global_load_dwordx4 v[94:97], v[136:137], off
	global_load_dwordx4 v[98:101], v[4:5], off offset:2048
	global_load_dwordx4 v[102:105], v[138:139], off
	global_load_dwordx4 v[106:109], v[140:141], off
	global_load_dwordx4 v[110:113], v[4:5], off offset:3072
	global_load_dwordx4 v[114:117], v[142:143], off
	global_load_dwordx4 v[118:121], v[144:145], off
	s_waitcnt vmcnt(15)
	v_mov_b32_e32 v70, v33
	s_waitcnt vmcnt(14)
	v_mov_b32_e32 v71, v37
	v_mov_b32_e32 v68, v32
	v_mov_b32_e32 v69, v36
	s_waitcnt vmcnt(13)
	v_mov_b32_e32 v78, v41
	s_waitcnt vmcnt(12)
	v_mov_b32_e32 v79, v45
	v_pk_mul_f32 v[70:71], v[70:71], v[70:71]
	v_mov_b32_e32 v64, v34
	v_mov_b32_e32 v65, v38
	v_mov_b32_e32 v76, v40
	v_mov_b32_e32 v77, v44
	v_pk_mul_f32 v[78:79], v[78:79], v[78:79]
	v_pk_fma_f32 v[68:69], v[68:69], v[68:69], v[70:71]
	v_mov_b32_e32 v66, v35
	v_mov_b32_e32 v67, v39
	v_mov_b32_e32 v72, v42
	v_mov_b32_e32 v73, v46
	v_pk_fma_f32 v[70:71], v[76:77], v[76:77], v[78:79]
	v_pk_fma_f32 v[64:65], v[64:65], v[64:65], v[68:69]
	v_mov_b32_e32 v74, v43
	v_mov_b32_e32 v75, v47
	v_pk_fma_f32 v[68:69], v[72:73], v[72:73], v[70:71]
	v_pk_fma_f32 v[64:65], v[66:67], v[66:67], v[64:65]
	v_pk_fma_f32 v[66:67], v[74:75], v[74:75], v[68:69]
	v_add_f32_e32 v11, v64, v65
	v_add_f32_e32 v11, v11, v66
	v_add_f32_e32 v11, v11, v67
	v_mov_b32_e32 v13, v11
	v_lshlrev_b64 v[64:65], 11, v[2:3]
	s_waitcnt vmcnt(11)
	v_pk_add_f32 v[48:49], v[48:49], 1.0 op_sel_hi:[1,0]
	v_pk_add_f32 v[50:51], v[50:51], 1.0 op_sel_hi:[1,0]
	v_lshl_add_u64 v[64:65], v[8:9], 0, v[64:65]
	s_nop 1
	v_permlane32_swap_b32_e32 v13, v11
	s_nop 0
	v_add_f32_e32 v11, v11, v13
	v_mov_b32_e32 v13, v11
	v_add_u32_e32 v2, s3, v2
	s_nop 1
	v_permlane16_swap_b32_e32 v13, v11
	s_nop 0
	v_add_f32_e32 v11, v11, v13
	s_nop 1
	v_add_f32_dpp v11, v11, v11 row_ror:8 row_mask:0xf bank_mask:0xf
	s_nop 1
	v_add_f32_dpp v11, v11, v11 row_ror:4 row_mask:0xf bank_mask:0xf
	s_nop 1
	v_add_f32_dpp v13, v11, v11 row_ror:2 row_mask:0xf bank_mask:0xf
	v_mov_b32_e32 v11, v1
	v_lshl_add_u64 v[66:67], v[60:61], 0, v[10:11]
	s_nop 1
	v_add_f32_dpp v3, v13, v13 row_ror:1 row_mask:0xf bank_mask:0xf
	v_fmamk_f32 v3, v3, 0x3a800000, v225
	v_mul_f32_e32 v13, 0x4b800000, v3
	v_cmp_gt_f32_e32 vcc, s33, v3
	v_mov_b32_e32 v15, v1
	s_nop 0
	v_cndmask_b32_e32 v3, v3, v13, vcc
	v_rsq_f32_e32 v3, v3
	s_nop 0
	v_mul_f32_e32 v13, 0x45800000, v3
	v_cndmask_b32_e32 v68, v3, v13, vcc
	v_pk_mul_f32 v[32:33], v[32:33], v[68:69] op_sel_hi:[1,0]
	v_pk_mul_f32 v[34:35], v[34:35], v[68:69] op_sel_hi:[1,0]
	s_waitcnt vmcnt(10)
	v_pk_mul_f32 v[32:33], v[52:53], v[32:33]
	v_pk_mul_f32 v[34:35], v[54:55], v[34:35]
	s_waitcnt vmcnt(0)
	v_pk_fma_f32 v[32:33], v[48:49], v[32:33], v[56:57]
	v_pk_fma_f32 v[34:35], v[50:51], v[34:35], v[58:59]
	v_cvt_pk_bf16_f32 v32, v32, v33
	v_cvt_pk_bf16_f32 v33, v34, v35
	global_store_dwordx2 v[64:65], v[32:33], off
	s_nop 0
	v_lshl_add_u64 v[52:53], v[62:63], 0, v[10:11]
	v_pk_mul_f32 v[36:37], v[36:37], v[68:69] op_sel_hi:[1,0]
	v_pk_mul_f32 v[38:39], v[38:39], v[68:69] op_sel_hi:[1,0]
	v_mov_b32_e32 v13, v1
	v_lshl_add_u64 v[56:57], v[60:61], 0, v[12:13]
	v_pk_mul_f32 v[40:41], v[40:41], v[68:69] op_sel_hi:[1,0]
	v_pk_mul_f32 v[42:43], v[42:43], v[68:69] op_sel_hi:[1,0]
	v_pk_mul_f32 v[44:45], v[44:45], v[68:69] op_sel_hi:[1,0]
	v_pk_mul_f32 v[46:47], v[46:47], v[68:69] op_sel_hi:[1,0]
	v_cmp_lt_i32_e32 vcc, s94, v2
	s_or_b64 s[26:27], vcc, s[26:27]
	v_pk_mul_f32 v[32:33], v[36:37], v[86:87]
	v_pk_add_f32 v[36:37], v[90:91], 1.0 op_sel_hi:[1,0]
	v_pk_mul_f32 v[34:35], v[38:39], v[88:89]
	v_pk_add_f32 v[38:39], v[92:93], 1.0 op_sel_hi:[1,0]
	v_pk_fma_f32 v[32:33], v[32:33], v[36:37], v[94:95]
	v_pk_fma_f32 v[34:35], v[34:35], v[38:39], v[96:97]
	v_cvt_pk_bf16_f32 v32, v32, v33
	v_cvt_pk_bf16_f32 v33, v34, v35
	global_store_dwordx2 v[64:65], v[32:33], off offset:512
	s_nop 0
	v_lshl_add_u64 v[48:49], v[62:63], 0, v[12:13]
	v_lshl_add_u64 v[52:53], v[60:61], 0, v[14:15]
	v_pk_mul_f32 v[32:33], v[40:41], v[98:99]
	v_pk_add_f32 v[36:37], v[102:103], 1.0 op_sel_hi:[1,0]
	v_pk_mul_f32 v[34:35], v[42:43], v[100:101]
	v_pk_add_f32 v[38:39], v[104:105], 1.0 op_sel_hi:[1,0]
	v_pk_fma_f32 v[32:33], v[32:33], v[36:37], v[106:107]
	v_pk_fma_f32 v[34:35], v[34:35], v[38:39], v[108:109]
	v_cvt_pk_bf16_f32 v32, v32, v33
	v_cvt_pk_bf16_f32 v33, v34, v35
	global_store_dwordx2 v[64:65], v[32:33], off offset:1024
	s_nop 0
	v_lshl_add_u64 v[40:41], v[62:63], 0, v[14:15]
	v_pk_mul_f32 v[32:33], v[44:45], v[110:111]
	v_pk_add_f32 v[36:37], v[114:115], 1.0 op_sel_hi:[1,0]
	v_pk_mul_f32 v[34:35], v[46:47], v[112:113]
	v_pk_add_f32 v[38:39], v[116:117], 1.0 op_sel_hi:[1,0]
	v_pk_fma_f32 v[32:33], v[32:33], v[36:37], v[118:119]
	v_pk_fma_f32 v[34:35], v[34:35], v[38:39], v[120:121]
	v_cvt_pk_bf16_f32 v32, v32, v33
	v_cvt_pk_bf16_f32 v33, v34, v35
	global_store_dwordx2 v[64:65], v[32:33], off offset:1536
	s_andn2_b64 exec, exec, s[26:27]
	s_cbranch_execnz .LBB0_597

; DI unsigned pack2(float a, float b) { f2_t v = {a, b}; return __builtin_bit_cast(unsigned, __builtin_convertvector(v, bf2_t)); }
; DI float wave_sum(float v) {
; #pragma unroll
;   for (int o = 32; o >= 1; o >>= 1) v += __shfl_xor(v, o);
;   return v;
; template <int MODE>
; DI void phase_norm(const float* xin, const float* g, const float* modl, int sh_off, int sc_off, u16* hout, float* fout) {
;     ...
;   for (int row = blockIdx.x * NWAVE + w; row < NTOK; row += gridDim.x * NWAVE) {
;     const int b = row >> 14;
;     const float4* xr = (const float4*)(xin + (size_t)row * 1024);
;     float4 v[4];
; #pragma unroll
;     for (int i = 0; i < 4; ++i) v[i] = xr[lane + i * 64];
;     float ss = 0.f;
; #pragma unroll
;     for (int i = 0; i < 4; ++i) ss += v[i].x * v[i].x + v[i].y * v[i].y + v[i].z * v[i].z + v[i].w * v[i].w;
;     ss = wave_sum(ss);
;     const float inv = rsqrtf(ss * (1.f / 1024.f) + 1e-6f);
; #pragma unroll
;     for (int i = 0; i < 4; ++i) {
;       const int col = (lane + i * 64) * 4;
;       const float4 g4 = *(const float4*)(g + col);
;       if (MODE == 0) {
;         const float4 sc4 = *(const float4*)(modl + b * 6144 + sc_off + col);
;         const float4 sh4 = *(const float4*)(modl + b * 6144 + sh_off + col);
;         float y0 = v[i].x * inv * g4.x * (1.f + sc4.x) + sh4.x;
;         float y1 = v[i].y * inv * g4.y * (1.f + sc4.y) + sh4.y;
;         float y2 = v[i].z * inv * g4.z * (1.f + sc4.z) + sh4.z;
;         float y3 = v[i].w * inv * g4.w * (1.f + sc4.w) + sh4.w;
;         *(uint2*)(hout + (size_t)row * 1024 + col) = make_uint2(pack2(y0, y1), pack2(y2, y3));
;       } else {
;         float4 y; y.x = v[i].x * inv * g4.x; y.y = v[i].y * inv * g4.y; y.z = v[i].z * inv * g4.z; y.w = v[i].w * inv * g4.w;
;         *(float4*)(fout + (size_t)row * 1024 + col) = y;
.LBB0_843:
	v_ashrrev_i32_e32 v1, 31, v0
	v_lshlrev_b64 v[10:11], 12, v[0:1]
	v_lshl_add_u64 v[30:31], s[6:7], 0, v[10:11]
	v_lshl_add_u64 v[32:33], v[30:31], 0, v[2:3]
	global_load_dwordx4 v[10:13], v[32:33], off
	global_load_dwordx4 v[14:17], v[32:33], off offset:1024
	global_load_dwordx4 v[18:21], v[32:33], off offset:2048
	global_load_dwordx4 v[22:25], v[32:33], off offset:3072
	v_lshl_add_u64 v[30:31], v[30:31], 0, v[6:7]
	v_add_u32_e32 v0, s3, v0
	s_waitcnt vmcnt(3)
	v_mov_b32_e32 v34, v11
	s_waitcnt vmcnt(2)
	v_mov_b32_e32 v35, v15
	v_mov_b32_e32 v32, v10
	v_mov_b32_e32 v33, v14
	s_waitcnt vmcnt(1)
	v_mov_b32_e32 v42, v19
	s_waitcnt vmcnt(0)
	v_mov_b32_e32 v43, v23
	v_pk_mul_f32 v[34:35], v[34:35], v[34:35]
	v_mov_b32_e32 v36, v12
	v_mov_b32_e32 v37, v16
	v_mov_b32_e32 v40, v18
	v_mov_b32_e32 v41, v22
	v_pk_mul_f32 v[42:43], v[42:43], v[42:43]
	v_pk_fma_f32 v[32:33], v[32:33], v[32:33], v[34:35]
	v_mov_b32_e32 v38, v13
	v_mov_b32_e32 v39, v17
	v_mov_b32_e32 v44, v20
	v_mov_b32_e32 v45, v24
	v_pk_fma_f32 v[34:35], v[40:41], v[40:41], v[42:43]
	v_pk_fma_f32 v[32:33], v[36:37], v[36:37], v[32:33]
	v_mov_b32_e32 v46, v21
	v_mov_b32_e32 v47, v25
	v_pk_fma_f32 v[34:35], v[44:45], v[44:45], v[34:35]
	v_pk_fma_f32 v[32:33], v[38:39], v[38:39], v[32:33]
	v_pk_fma_f32 v[34:35], v[46:47], v[46:47], v[34:35]
	v_add_f32_e32 v1, v32, v33
	v_add_f32_e32 v1, v1, v34
	v_add_f32_e32 v1, v1, v35
	v_mov_b32_e32 v9, v1
	s_nop 1
	v_permlane32_swap_b32_e32 v9, v1
	s_nop 0
	v_add_f32_e32 v1, v1, v9
	v_mov_b32_e32 v9, v1
	s_nop 1
	v_permlane16_swap_b32_e32 v9, v1
	s_nop 0
	v_add_f32_e32 v1, v1, v9
	s_nop 1
	v_add_f32_dpp v1, v1, v1 row_ror:8 row_mask:0xf bank_mask:0xf
	s_nop 1
	v_add_f32_dpp v1, v1, v1 row_ror:4 row_mask:0xf bank_mask:0xf
	s_nop 1
	v_add_f32_dpp v1, v1, v1 row_ror:2 row_mask:0xf bank_mask:0xf
	s_nop 1
	v_add_f32_dpp v1, v1, v1 row_ror:1 row_mask:0xf bank_mask:0xf
	v_fmamk_f32 v1, v1, 0x3a800000, v8
	v_mul_f32_e32 v9, 0x4b800000, v1
	v_cmp_gt_f32_e32 vcc, s2, v1
	s_nop 1
	v_cndmask_b32_e32 v1, v1, v9, vcc
	v_rsq_f32_e32 v1, v1
	s_nop 0
	v_mul_f32_e32 v9, 0x45800000, v1
	v_cndmask_b32_e32 v32, v1, v9, vcc
	v_pk_mul_f32 v[10:11], v[10:11], v[32:33] op_sel_hi:[1,0]
	v_pk_mul_f32 v[12:13], v[12:13], v[32:33] op_sel_hi:[1,0]
	v_pk_mul_f32 v[10:11], v[48:49], v[10:11]
	v_pk_mul_f32 v[12:13], v[50:51], v[12:13]
	global_store_dwordx4 v[30:31], v[10:13], off
	s_nop 1
	v_pk_mul_f32 v[14:15], v[14:15], v[32:33] op_sel_hi:[1,0]
	v_pk_mul_f32 v[16:17], v[16:17], v[32:33] op_sel_hi:[1,0]
	v_cmp_lt_i32_e32 vcc, s4, v0
	s_or_b64 s[0:1], vcc, s[0:1]
	v_pk_mul_f32 v[10:11], v[52:53], v[14:15]
	v_pk_mul_f32 v[12:13], v[54:55], v[16:17]
	global_store_dwordx4 v[30:31], v[10:13], off offset:1024
	s_nop 1
	v_pk_mul_f32 v[14:15], v[18:19], v[32:33] op_sel_hi:[1,0]
	v_pk_mul_f32 v[16:17], v[20:21], v[32:33] op_sel_hi:[1,0]
	v_pk_mul_f32 v[10:11], v[14:15], v[56:57]
	v_pk_mul_f32 v[12:13], v[16:17], v[58:59]
	global_store_dwordx4 v[30:31], v[10:13], off offset:2048
	s_nop 1
	v_pk_mul_f32 v[14:15], v[22:23], v[32:33] op_sel_hi:[1,0]
	v_pk_mul_f32 v[16:17], v[24:25], v[32:33] op_sel_hi:[1,0]
	v_pk_mul_f32 v[10:11], v[14:15], v[60:61]
	v_pk_mul_f32 v[12:13], v[16:17], v[62:63]
	global_store_dwordx4 v[30:31], v[10:13], off offset:3072
	s_nop 1
	s_andn2_b64 exec, exec, s[0:1]
	s_cbranch_execnz .LBB0_843
